# GEMM unit transitions: removed the two epilogue-alignment barriers (leading half's epilogue now overlaps the trailing half's last MFMA block); exit parity kept by taking the extra barrier only after t
# baseline (speedup 1.0000x reference)
; __device__ __forceinline__ unsigned cvt_pk_bf16(float lo, float hi) { f32x2_t v = {lo, hi}; bf16x2_t b = __builtin_convertvector(v, bf16x2_t); return __builtin_bit_cast(unsigned, b); }
; #define PG8_BAR __builtin_amdgcn_s_barrier()
;     __device__ __forceinline__ void operator()(const f32x4 (&acc)[2][2][4][2], const Unit& u, int wr, int wc, int fr, int fq) const {
;         const int row0 = u.pm * BM + wr * 64 + fr, col0 = u.pn * BM + wc * 32 + 8 * fq;
; #pragma unroll
;         for (int ai = 0; ai < 2; ++ai)
; #pragma unroll
;             for (int m = 0; m < 4; ++m) { bf16_t* rowp = O + (size_t)(row0 + ai * HALF + m * 16) * ldc + col0;
; #pragma unroll
;                 for (int bj = 0; bj < 2; ++bj) { const f32x4 v0 = acc[ai][bj][m][0], v1 = acc[ai][bj][m][1];
;                     u32x4 w; w.x = cvt_pk_bf16(v0[0], v0[1]); w.y = cvt_pk_bf16(v0[2], v0[3]); w.z = cvt_pk_bf16(v1[0], v1[1]); w.w = cvt_pk_bf16(v1[2], v1[3]);
;                     *(u32x4*)(rowp + bj * HALF) = w; } }
;     }
; template <class Epi, class Sched, bool ALIGN_EPI = false, bool SP2 = false>
; __device__ __forceinline__ void gemm_phase(PG8_LAS unsigned char* lds, const Gemm g, const Sched& S, const Epi& E) {
;     ...
;         if constexpr (ALIGN_EPI) { if (wr == 0) PG8_BAR; }
;         if constexpr (!Epi::AFTER_DRAIN) { E(acc, cur, wr, wc, fr, fq); S.done(cur); }
;         if (!has_next) break;
; #pragma unroll
;         for (int a = 0; a < 2; ++a)
; #pragma unroll
;             for (int b = 0; b < 2; ++b)
; #pragma unroll
;                 for (int m = 0; m < 4; ++m)
; #pragma unroll
;                     for (int n = 0; n < 2; ++n) acc[a][b][m][n] = (f32x4){0.f, 0.f, 0.f, 0.f};
;         cur = nxt; cA = nA; cB = nB; ++ui;
;         if constexpr (ALIGN_EPI) { if (wr == 1) PG8_BAR; }
.Lpeel_after_A:
	s_and_b64 vcc, exec, s[6:7]
	s_cbranch_vccz .LBB0_236
	s_and_b64 vcc, exec, s[16:17]
	s_cbranch_vccz .LBB0_236
	s_barrier
.LBB0_236:
	v_lshl_add_u32 v175, s42, 8, v171
	v_lshl_or_b32 v176, s51, 8, v173
	v_ashrrev_i32_e32 v177, 31, v176
	v_mad_i64_i32 v[178:179], s[20:21], v175, s1, 0
	v_cvt_pk_bf16_f32 v110, v110, v111
	v_cvt_pk_bf16_f32 v111, v112, v113
	v_cvt_pk_bf16_f32 v112, v106, v107
	v_or_b32_e32 v106, 16, v175
	v_lshl_add_u64 v[178:179], v[178:179], 1, s[14:15]
	v_lshlrev_b64 v[176:177], 1, v[176:177]
	v_mad_i64_i32 v[106:107], s[20:21], v106, s1, 0
	v_cvt_pk_bf16_f32 v94, v94, v95
	v_cvt_pk_bf16_f32 v95, v96, v97
	v_cvt_pk_bf16_f32 v96, v90, v91
	v_or_b32_e32 v90, 32, v175
	v_lshl_add_u64 v[178:179], v[178:179], 0, v[176:177]
	v_cvt_pk_bf16_f32 v113, v108, v109
	v_lshl_add_u64 v[106:107], v[106:107], 1, s[14:15]
	v_mad_i64_i32 v[90:91], s[20:21], v90, s1, 0
	v_cvt_pk_bf16_f32 v78, v78, v79
	v_cvt_pk_bf16_f32 v79, v80, v81
	v_cvt_pk_bf16_f32 v80, v74, v75
	v_or_b32_e32 v74, 48, v175
	v_cvt_pk_bf16_f32 v70, v70, v71
	v_cvt_pk_bf16_f32 v71, v72, v73
	v_cvt_pk_bf16_f32 v72, v66, v67
	v_add_u32_e32 v66, 0x80, v175
	v_cvt_pk_bf16_f32 v126, v126, v127
	v_cvt_pk_bf16_f32 v127, v128, v129
	v_cvt_pk_bf16_f32 v128, v122, v123
	v_cvt_pk_bf16_f32 v129, v124, v125
	global_store_dwordx4 v[178:179], v[110:113], off offset:256
	v_cvt_pk_bf16_f32 v97, v92, v93
	v_lshl_add_u64 v[90:91], v[90:91], 1, s[14:15]
	v_lshl_add_u64 v[110:111], v[106:107], 0, v[176:177]
	v_mad_i64_i32 v[74:75], s[20:21], v74, s1, 0
	v_mad_i64_i32 v[66:67], s[20:21], v66, s1, 0
	v_cvt_pk_bf16_f32 v46, v46, v47
	v_cvt_pk_bf16_f32 v47, v48, v49
	v_cvt_pk_bf16_f32 v48, v42, v43
	v_add_u32_e32 v42, 0x90, v175
	global_store_dwordx4 v[178:179], v[126:129], off
	v_cvt_pk_bf16_f32 v106, v118, v119
	v_cvt_pk_bf16_f32 v107, v120, v121
	v_cvt_pk_bf16_f32 v108, v114, v115
	v_cvt_pk_bf16_f32 v109, v116, v117
	global_store_dwordx4 v[110:111], v[94:97], off offset:256
	v_cvt_pk_bf16_f32 v81, v76, v77
	v_lshl_add_u64 v[74:75], v[74:75], 1, s[14:15]
	v_lshl_add_u64 v[94:95], v[90:91], 0, v[176:177]
	v_lshl_add_u64 v[66:67], v[66:67], 1, s[14:15]
	v_mad_i64_i32 v[42:43], s[20:21], v42, s1, 0
	v_cvt_pk_bf16_f32 v30, v30, v31
	v_cvt_pk_bf16_f32 v31, v32, v33
	v_cvt_pk_bf16_f32 v32, v26, v27
	v_add_u32_e32 v26, 0xa0, v175
	global_store_dwordx4 v[110:111], v[106:109], off
	v_cvt_pk_bf16_f32 v90, v102, v103
	v_cvt_pk_bf16_f32 v91, v104, v105
	v_cvt_pk_bf16_f32 v92, v98, v99
	v_cvt_pk_bf16_f32 v93, v100, v101
	global_store_dwordx4 v[94:95], v[78:81], off offset:256
	v_cvt_pk_bf16_f32 v76, v82, v83
	v_cvt_pk_bf16_f32 v77, v84, v85
	v_lshl_add_u64 v[78:79], v[74:75], 0, v[176:177]
	v_cvt_pk_bf16_f32 v74, v86, v87
	v_cvt_pk_bf16_f32 v75, v88, v89
	v_cvt_pk_bf16_f32 v73, v68, v69
	v_lshl_add_u64 v[66:67], v[66:67], 0, v[176:177]
	v_cvt_pk_bf16_f32 v49, v44, v45
	v_lshl_add_u64 v[42:43], v[42:43], 1, s[14:15]
	v_mad_i64_i32 v[26:27], s[20:21], v26, s1, 0
	v_cvt_pk_bf16_f32 v14, v14, v15
	v_cvt_pk_bf16_f32 v15, v16, v17
	v_cvt_pk_bf16_f32 v16, v10, v11
	v_add_u32_e32 v10, 0xb0, v175
	global_store_dwordx4 v[94:95], v[90:93], off
	global_store_dwordx4 v[78:79], v[74:77], off
	global_store_dwordx4 v[78:79], v[70:73], off offset:256
	v_cvt_pk_bf16_f32 v62, v62, v63
	v_cvt_pk_bf16_f32 v63, v64, v65
	v_cvt_pk_bf16_f32 v64, v58, v59
	v_cvt_pk_bf16_f32 v65, v60, v61
	global_store_dwordx4 v[66:67], v[46:49], off offset:256
	v_cvt_pk_bf16_f32 v33, v28, v29
	v_lshl_add_u64 v[26:27], v[26:27], 1, s[14:15]
	v_lshl_add_u64 v[46:47], v[42:43], 0, v[176:177]
	v_mad_i64_i32 v[10:11], s[20:21], v10, s1, 0
	global_store_dwordx4 v[66:67], v[62:65], off
	v_cvt_pk_bf16_f32 v42, v54, v55
	v_cvt_pk_bf16_f32 v43, v56, v57
	v_cvt_pk_bf16_f32 v44, v50, v51
	v_cvt_pk_bf16_f32 v45, v52, v53
	global_store_dwordx4 v[46:47], v[30:33], off offset:256
	v_cvt_pk_bf16_f32 v17, v12, v13
	v_lshl_add_u64 v[10:11], v[10:11], 1, s[14:15]
	v_lshl_add_u64 v[30:31], v[26:27], 0, v[176:177]
	global_store_dwordx4 v[46:47], v[42:45], off
	v_cvt_pk_bf16_f32 v26, v38, v39
	v_cvt_pk_bf16_f32 v27, v40, v41
	v_cvt_pk_bf16_f32 v28, v34, v35
	v_cvt_pk_bf16_f32 v29, v36, v37
	global_store_dwordx4 v[30:31], v[14:17], off offset:256
	v_cvt_pk_bf16_f32 v12, v18, v19
	v_cvt_pk_bf16_f32 v13, v20, v21
	v_lshl_add_u64 v[14:15], v[10:11], 0, v[176:177]
	v_cvt_pk_bf16_f32 v10, v22, v23
	v_cvt_pk_bf16_f32 v11, v24, v25
	v_cvt_pk_bf16_f32 v6, v6, v7
	v_cvt_pk_bf16_f32 v7, v8, v9
	v_cvt_pk_bf16_f32 v8, v2, v3
	v_cvt_pk_bf16_f32 v9, v4, v5
	s_and_b64 vcc, exec, s[6:7]
	s_mov_b64 s[6:7], -1
	global_store_dwordx4 v[30:31], v[26:29], off
	global_store_dwordx4 v[14:15], v[10:13], off
	global_store_dwordx4 v[14:15], v[6:9], off offset:256
	s_cbranch_vccnz .LBB0_225
	s_branch .LBB0_224

; __device__ __forceinline__ unsigned cvt_pk_bf16(float lo, float hi) { f32x2_t v = {lo, hi}; bf16x2_t b = __builtin_convertvector(v, bf16x2_t); return __builtin_bit_cast(unsigned, b); }
; __device__ __forceinline__ float fsigmoid(float x) { return __builtin_amdgcn_rcpf(1.0f + __expf(-x)); }
; #define PG8_BAR __builtin_amdgcn_s_barrier()
;     __device__ __forceinline__ void operator()(const f32x4 (&acc)[2][2][4][2], const Unit& u, int wr, int wc, int fr, int fq) const {
;         const int row0 = u.pm * BM + wr * 64 + fr, col0 = u.pn * HALF + wc * 32 + 8 * fq;
; #pragma unroll
;         for (int ai = 0; ai < 2; ++ai)
; #pragma unroll
;             for (int m = 0; m < 4; ++m) { bf16_t* rowp = O + (size_t)(row0 + ai * HALF + m * 16) * ldc + col0;
;                 float v[8];
; #pragma unroll
;                 for (int n = 0; n < 2; ++n)
; #pragma unroll
;                     for (int j = 0; j < 4; ++j) { const float g = acc[ai][0][m][n][j], up = acc[ai][1][m][n][j]; v[n * 4 + j] = g * fsigmoid(g) * up; }
;                 u32x4 w; w.x = cvt_pk_bf16(v[0], v[1]); w.y = cvt_pk_bf16(v[2], v[3]); w.z = cvt_pk_bf16(v[4], v[5]); w.w = cvt_pk_bf16(v[6], v[7]);
;                 *(u32x4*)rowp = w; }
; template <class Epi, class Sched, bool ALIGN_EPI = false, bool SP2 = false>
; __device__ __forceinline__ void gemm_phase(PG8_LAS unsigned char* lds, const Gemm g, const Sched& S, const Epi& E) {
;     ...
;         if constexpr (ALIGN_EPI) { if (wr == 0) PG8_BAR; }
;         if constexpr (!Epi::AFTER_DRAIN) { E(acc, cur, wr, wc, fr, fq); S.done(cur); }
.Lpeel_after_B:
	s_andn2_b64 vcc, exec, s[6:7]
	s_cbranch_vccz .LBB0_287
	s_and_b64 vcc, exec, s[10:11]
	s_cbranch_vccz .LBB0_287
	s_barrier
.LBB0_287:
	v_mul_f32_e32 v144, 0xbfb8aa3b, v126
	v_exp_f32_e32 v144, v144
	v_mul_f32_e32 v145, 0xbfb8aa3b, v127
	v_exp_f32_e32 v145, v145
	v_lshl_or_b32 v150, s36, 7, v147
	v_add_f32_e32 v144, 1.0, v144
	v_rcp_f32_e32 v152, v144
	v_add_f32_e32 v144, 1.0, v145
	v_rcp_f32_e32 v153, v144
	v_lshl_add_u32 v149, s37, 8, v0
	v_ashrrev_i32_e32 v151, 31, v150
	v_mov_b64_e32 v[144:145], s[94:95]
	v_pk_mul_f32 v[126:127], v[126:127], v[152:153]
	v_mul_f32_e32 v152, 0xbfb8aa3b, v128
	v_mul_f32_e32 v153, 0xbfb8aa3b, v129
	v_exp_f32_e32 v152, v152
	v_exp_f32_e32 v153, v153
	v_pk_mul_f32 v[118:119], v[126:127], v[118:119]
	v_mad_i64_i32 v[172:173], s[20:21], v149, s98, v[144:145]
	v_add_f32_e32 v126, 1.0, v152
	v_add_f32_e32 v127, 1.0, v153
	v_mul_f32_e32 v152, 0xbfb8aa3b, v122
	v_mul_f32_e32 v153, 0xbfb8aa3b, v123
	v_rcp_f32_e32 v126, v126
	v_rcp_f32_e32 v127, v127
	v_exp_f32_e32 v152, v152
	v_exp_f32_e32 v153, v153
	s_andn2_b64 vcc, exec, s[6:7]
	v_pk_mul_f32 v[126:127], v[128:129], v[126:127]
	v_add_f32_e32 v128, 1.0, v152
	v_add_f32_e32 v129, 1.0, v153
	v_mul_f32_e32 v152, 0xbfb8aa3b, v124
	v_mul_f32_e32 v153, 0xbfb8aa3b, v125
	v_exp_f32_e32 v152, v152
	v_exp_f32_e32 v153, v153
	v_rcp_f32_e32 v128, v128
	v_rcp_f32_e32 v129, v129
	v_add_f32_e32 v152, 1.0, v152
	v_add_f32_e32 v153, 1.0, v153
	v_rcp_f32_e32 v152, v152
	v_rcp_f32_e32 v153, v153
	v_pk_mul_f32 v[122:123], v[122:123], v[128:129]
	v_pk_mul_f32 v[120:121], v[126:127], v[120:121]
	v_pk_mul_f32 v[122:123], v[122:123], v[114:115]
	v_pk_mul_f32 v[114:115], v[124:125], v[152:153]
	s_mov_b64 s[6:7], -1
	v_pk_mul_f32 v[124:125], v[114:115], v[116:117]
	v_cvt_pk_bf16_f32 v117, v120, v121
	v_mul_f32_e32 v120, 0xbfb8aa3b, v110
	v_mul_f32_e32 v121, 0xbfb8aa3b, v111
	v_exp_f32_e32 v120, v120
	v_exp_f32_e32 v121, v121
	v_lshlrev_b64 v[114:115], 1, v[150:151]
	v_lshl_add_u64 v[126:127], v[172:173], 0, v[114:115]
	v_cvt_pk_bf16_f32 v116, v118, v119
	v_cvt_pk_bf16_f32 v118, v122, v123
	v_cvt_pk_bf16_f32 v119, v124, v125
	global_store_dwordx4 v[126:127], v[116:119], off
	s_nop 1
	v_add_f32_e32 v116, 1.0, v120
	v_add_f32_e32 v117, 1.0, v121
	v_rcp_f32_e32 v116, v116
	v_rcp_f32_e32 v117, v117
	v_or_b32_e32 v118, 16, v149
	v_mad_i64_i32 v[118:119], s[20:21], v118, s98, v[144:145]
	v_pk_mul_f32 v[110:111], v[110:111], v[116:117]
	v_mul_f32_e32 v116, 0xbfb8aa3b, v112
	v_mul_f32_e32 v117, 0xbfb8aa3b, v113
	v_exp_f32_e32 v116, v116
	v_exp_f32_e32 v117, v117
	v_pk_mul_f32 v[102:103], v[110:111], v[102:103]
	v_add_f32_e32 v110, 1.0, v116
	v_add_f32_e32 v111, 1.0, v117
	v_mul_f32_e32 v116, 0xbfb8aa3b, v106
	v_mul_f32_e32 v117, 0xbfb8aa3b, v107
	v_rcp_f32_e32 v110, v110
	v_rcp_f32_e32 v111, v111
	v_exp_f32_e32 v116, v116
	v_exp_f32_e32 v117, v117
	v_pk_mul_f32 v[110:111], v[112:113], v[110:111]
	v_add_f32_e32 v112, 1.0, v116
	v_add_f32_e32 v113, 1.0, v117
	v_mul_f32_e32 v116, 0xbfb8aa3b, v108
	v_mul_f32_e32 v117, 0xbfb8aa3b, v109
	v_exp_f32_e32 v116, v116
	v_exp_f32_e32 v117, v117
	v_rcp_f32_e32 v112, v112
	v_rcp_f32_e32 v113, v113
	v_add_f32_e32 v116, 1.0, v116
	v_add_f32_e32 v117, 1.0, v117
	v_rcp_f32_e32 v116, v116
	v_rcp_f32_e32 v117, v117
	v_pk_mul_f32 v[106:107], v[106:107], v[112:113]
	v_pk_mul_f32 v[104:105], v[110:111], v[104:105]
	v_pk_mul_f32 v[106:107], v[106:107], v[98:99]
	v_pk_mul_f32 v[98:99], v[108:109], v[116:117]
	v_lshl_add_u64 v[110:111], v[118:119], 0, v[114:115]
	v_pk_mul_f32 v[108:109], v[98:99], v[100:101]
	v_cvt_pk_bf16_f32 v98, v102, v103
	v_mul_f32_e32 v102, 0xbfb8aa3b, v94
	v_mul_f32_e32 v103, 0xbfb8aa3b, v95
	v_exp_f32_e32 v102, v102
	v_exp_f32_e32 v103, v103
	v_cvt_pk_bf16_f32 v99, v104, v105
	v_cvt_pk_bf16_f32 v100, v106, v107
	v_cvt_pk_bf16_f32 v101, v108, v109
	global_store_dwordx4 v[110:111], v[98:101], off
	s_nop 1
	v_add_f32_e32 v98, 1.0, v102
	v_add_f32_e32 v99, 1.0, v103
	v_rcp_f32_e32 v98, v98
	v_rcp_f32_e32 v99, v99
	v_or_b32_e32 v100, 32, v149
	v_mad_i64_i32 v[100:101], s[20:21], v100, s98, v[144:145]
	v_pk_mul_f32 v[94:95], v[94:95], v[98:99]
	v_mul_f32_e32 v98, 0xbfb8aa3b, v96
	v_mul_f32_e32 v99, 0xbfb8aa3b, v97
	v_exp_f32_e32 v98, v98
	v_exp_f32_e32 v99, v99
	v_pk_mul_f32 v[86:87], v[94:95], v[86:87]
	v_add_f32_e32 v94, 1.0, v98
	v_add_f32_e32 v95, 1.0, v99
	v_mul_f32_e32 v98, 0xbfb8aa3b, v90
	v_mul_f32_e32 v99, 0xbfb8aa3b, v91
	v_rcp_f32_e32 v94, v94
	v_rcp_f32_e32 v95, v95
	v_exp_f32_e32 v98, v98
	v_exp_f32_e32 v99, v99
	v_pk_mul_f32 v[94:95], v[96:97], v[94:95]
	v_add_f32_e32 v96, 1.0, v98
	v_add_f32_e32 v97, 1.0, v99
	v_mul_f32_e32 v98, 0xbfb8aa3b, v92
	v_mul_f32_e32 v99, 0xbfb8aa3b, v93
	v_exp_f32_e32 v98, v98
	v_exp_f32_e32 v99, v99
	v_rcp_f32_e32 v96, v96
	v_rcp_f32_e32 v97, v97
	v_add_f32_e32 v98, 1.0, v98
	v_add_f32_e32 v99, 1.0, v99
	v_rcp_f32_e32 v98, v98
	v_rcp_f32_e32 v99, v99
	v_pk_mul_f32 v[90:91], v[90:91], v[96:97]
	v_pk_mul_f32 v[88:89], v[94:95], v[88:89]
	v_pk_mul_f32 v[90:91], v[90:91], v[82:83]
	v_pk_mul_f32 v[82:83], v[92:93], v[98:99]
	v_lshl_add_u64 v[94:95], v[100:101], 0, v[114:115]
	v_pk_mul_f32 v[92:93], v[82:83], v[84:85]
	v_cvt_pk_bf16_f32 v82, v86, v87
	v_mul_f32_e32 v86, 0xbfb8aa3b, v78
	v_mul_f32_e32 v87, 0xbfb8aa3b, v79
	v_exp_f32_e32 v86, v86
	v_exp_f32_e32 v87, v87
	v_cvt_pk_bf16_f32 v83, v88, v89
	v_cvt_pk_bf16_f32 v84, v90, v91
	v_cvt_pk_bf16_f32 v85, v92, v93
	global_store_dwordx4 v[94:95], v[82:85], off
	s_nop 1
	v_add_f32_e32 v82, 1.0, v86
	v_add_f32_e32 v83, 1.0, v87
	v_rcp_f32_e32 v82, v82
	v_rcp_f32_e32 v83, v83
	v_or_b32_e32 v84, 48, v149
	v_mad_i64_i32 v[84:85], s[20:21], v84, s98, v[144:145]
; __device__ __forceinline__ unsigned cvt_pk_bf16(float lo, float hi) { f32x2_t v = {lo, hi}; bf16x2_t b = __builtin_convertvector(v, bf16x2_t); return __builtin_bit_cast(unsigned, b); }
; __device__ __forceinline__ float fsigmoid(float x) { return __builtin_amdgcn_rcpf(1.0f + __expf(-x)); }
;     __device__ __forceinline__ void operator()(const f32x4 (&acc)[2][2][4][2], const Unit& u, int wr, int wc, int fr, int fq) const {
;         const int row0 = u.pm * BM + wr * 64 + fr, col0 = u.pn * HALF + wc * 32 + 8 * fq;
; #pragma unroll
;         for (int ai = 0; ai < 2; ++ai)
; #pragma unroll
;             for (int m = 0; m < 4; ++m) { bf16_t* rowp = O + (size_t)(row0 + ai * HALF + m * 16) * ldc + col0;
;                 float v[8];
; #pragma unroll
;                 for (int n = 0; n < 2; ++n)
; #pragma unroll
;                     for (int j = 0; j < 4; ++j) { const float g = acc[ai][0][m][n][j], up = acc[ai][1][m][n][j]; v[n * 4 + j] = g * fsigmoid(g) * up; }
;                 u32x4 w; w.x = cvt_pk_bf16(v[0], v[1]); w.y = cvt_pk_bf16(v[2], v[3]); w.z = cvt_pk_bf16(v[4], v[5]); w.w = cvt_pk_bf16(v[6], v[7]);
;                 *(u32x4*)rowp = w; }
	v_pk_mul_f32 v[78:79], v[78:79], v[82:83]
	v_mul_f32_e32 v82, 0xbfb8aa3b, v80
	v_mul_f32_e32 v83, 0xbfb8aa3b, v81
	v_exp_f32_e32 v82, v82
	v_exp_f32_e32 v83, v83
	v_pk_mul_f32 v[70:71], v[78:79], v[70:71]
	v_add_f32_e32 v78, 1.0, v82
	v_add_f32_e32 v79, 1.0, v83
	v_mul_f32_e32 v82, 0xbfb8aa3b, v74
	v_mul_f32_e32 v83, 0xbfb8aa3b, v75
	v_rcp_f32_e32 v78, v78
	v_rcp_f32_e32 v79, v79
	v_exp_f32_e32 v82, v82
	v_exp_f32_e32 v83, v83
	v_pk_mul_f32 v[78:79], v[80:81], v[78:79]
	v_add_f32_e32 v80, 1.0, v82
	v_add_f32_e32 v81, 1.0, v83
	v_mul_f32_e32 v82, 0xbfb8aa3b, v76
	v_mul_f32_e32 v83, 0xbfb8aa3b, v77
	v_exp_f32_e32 v82, v82
	v_exp_f32_e32 v83, v83
	v_rcp_f32_e32 v80, v80
	v_rcp_f32_e32 v81, v81
	v_add_f32_e32 v82, 1.0, v82
	v_add_f32_e32 v83, 1.0, v83
	v_rcp_f32_e32 v82, v82
	v_rcp_f32_e32 v83, v83
	v_pk_mul_f32 v[74:75], v[74:75], v[80:81]
	v_pk_mul_f32 v[72:73], v[78:79], v[72:73]
	v_pk_mul_f32 v[74:75], v[74:75], v[66:67]
	v_pk_mul_f32 v[66:67], v[76:77], v[82:83]
	v_lshl_add_u64 v[78:79], v[84:85], 0, v[114:115]
	v_pk_mul_f32 v[76:77], v[66:67], v[68:69]
	v_cvt_pk_bf16_f32 v66, v70, v71
	v_mul_f32_e32 v70, 0xbfb8aa3b, v62
	v_mul_f32_e32 v71, 0xbfb8aa3b, v63
	v_exp_f32_e32 v70, v70
	v_exp_f32_e32 v71, v71
	v_cvt_pk_bf16_f32 v67, v72, v73
	v_cvt_pk_bf16_f32 v68, v74, v75
	v_cvt_pk_bf16_f32 v69, v76, v77
	global_store_dwordx4 v[78:79], v[66:69], off
	s_nop 1
	v_add_f32_e32 v66, 1.0, v70
	v_add_f32_e32 v67, 1.0, v71
	v_rcp_f32_e32 v66, v66
	v_rcp_f32_e32 v67, v67
	v_add_u32_e32 v68, 0x80, v149
	v_mad_i64_i32 v[68:69], s[20:21], v68, s98, v[144:145]
	v_pk_mul_f32 v[62:63], v[62:63], v[66:67]
	v_mul_f32_e32 v66, 0xbfb8aa3b, v64
	v_mul_f32_e32 v67, 0xbfb8aa3b, v65
	v_exp_f32_e32 v66, v66
	v_exp_f32_e32 v67, v67
	v_pk_mul_f32 v[54:55], v[62:63], v[54:55]
	v_add_f32_e32 v62, 1.0, v66
	v_add_f32_e32 v63, 1.0, v67
	v_mul_f32_e32 v66, 0xbfb8aa3b, v58
	v_mul_f32_e32 v67, 0xbfb8aa3b, v59
	v_rcp_f32_e32 v62, v62
	v_rcp_f32_e32 v63, v63
	v_exp_f32_e32 v66, v66
	v_exp_f32_e32 v67, v67
	v_pk_mul_f32 v[62:63], v[64:65], v[62:63]
	v_add_f32_e32 v64, 1.0, v66
	v_add_f32_e32 v65, 1.0, v67
	v_mul_f32_e32 v66, 0xbfb8aa3b, v60
	v_mul_f32_e32 v67, 0xbfb8aa3b, v61
	v_exp_f32_e32 v66, v66
	v_exp_f32_e32 v67, v67
	v_rcp_f32_e32 v64, v64
	v_rcp_f32_e32 v65, v65
	v_add_f32_e32 v66, 1.0, v66
	v_add_f32_e32 v67, 1.0, v67
	v_rcp_f32_e32 v66, v66
	v_rcp_f32_e32 v67, v67
	v_pk_mul_f32 v[58:59], v[58:59], v[64:65]
	v_pk_mul_f32 v[56:57], v[62:63], v[56:57]
	v_pk_mul_f32 v[58:59], v[58:59], v[50:51]
	v_pk_mul_f32 v[50:51], v[60:61], v[66:67]
	v_lshl_add_u64 v[62:63], v[68:69], 0, v[114:115]
	v_pk_mul_f32 v[60:61], v[50:51], v[52:53]
	v_cvt_pk_bf16_f32 v50, v54, v55
	v_mul_f32_e32 v54, 0xbfb8aa3b, v46
	v_mul_f32_e32 v55, 0xbfb8aa3b, v47
	v_exp_f32_e32 v54, v54
	v_exp_f32_e32 v55, v55
	v_cvt_pk_bf16_f32 v51, v56, v57
	v_cvt_pk_bf16_f32 v52, v58, v59
	v_cvt_pk_bf16_f32 v53, v60, v61
	global_store_dwordx4 v[62:63], v[50:53], off
	s_nop 1
	v_add_f32_e32 v50, 1.0, v54
	v_add_f32_e32 v51, 1.0, v55
	v_rcp_f32_e32 v50, v50
	v_rcp_f32_e32 v51, v51
	v_add_u32_e32 v52, 0x90, v149
	v_mad_i64_i32 v[52:53], s[20:21], v52, s98, v[144:145]
	v_pk_mul_f32 v[46:47], v[46:47], v[50:51]
	v_mul_f32_e32 v50, 0xbfb8aa3b, v48
	v_mul_f32_e32 v51, 0xbfb8aa3b, v49
	v_exp_f32_e32 v50, v50
	v_exp_f32_e32 v51, v51
	v_pk_mul_f32 v[38:39], v[46:47], v[38:39]
	v_add_f32_e32 v46, 1.0, v50
	v_add_f32_e32 v47, 1.0, v51
	v_mul_f32_e32 v50, 0xbfb8aa3b, v42
	v_mul_f32_e32 v51, 0xbfb8aa3b, v43
	v_rcp_f32_e32 v46, v46
	v_rcp_f32_e32 v47, v47
	v_exp_f32_e32 v50, v50
	v_exp_f32_e32 v51, v51
	v_pk_mul_f32 v[46:47], v[48:49], v[46:47]
	v_add_f32_e32 v48, 1.0, v50
	v_add_f32_e32 v49, 1.0, v51
	v_mul_f32_e32 v50, 0xbfb8aa3b, v44
	v_mul_f32_e32 v51, 0xbfb8aa3b, v45
	v_exp_f32_e32 v50, v50
; __device__ __forceinline__ unsigned cvt_pk_bf16(float lo, float hi) { f32x2_t v = {lo, hi}; bf16x2_t b = __builtin_convertvector(v, bf16x2_t); return __builtin_bit_cast(unsigned, b); }
; __device__ __forceinline__ float fsigmoid(float x) { return __builtin_amdgcn_rcpf(1.0f + __expf(-x)); }
; #define PG8_BAR __builtin_amdgcn_s_barrier()
;     __device__ __forceinline__ void operator()(const f32x4 (&acc)[2][2][4][2], const Unit& u, int wr, int wc, int fr, int fq) const {
;     ...
;             for (int m = 0; m < 4; ++m) { bf16_t* rowp = O + (size_t)(row0 + ai * HALF + m * 16) * ldc + col0;
;                 float v[8];
; #pragma unroll
;                 for (int n = 0; n < 2; ++n)
; #pragma unroll
;                     for (int j = 0; j < 4; ++j) { const float g = acc[ai][0][m][n][j], up = acc[ai][1][m][n][j]; v[n * 4 + j] = g * fsigmoid(g) * up; }
;                 u32x4 w; w.x = cvt_pk_bf16(v[0], v[1]); w.y = cvt_pk_bf16(v[2], v[3]); w.z = cvt_pk_bf16(v[4], v[5]); w.w = cvt_pk_bf16(v[6], v[7]);
;                 *(u32x4*)rowp = w; }
; template <class Epi, class Sched, bool ALIGN_EPI = false, bool SP2 = false>
; __device__ __forceinline__ void gemm_phase(PG8_LAS unsigned char* lds, const Gemm g, const Sched& S, const Epi& E) {
;     ...
;         if (!has_next) break;
; #pragma unroll
;         for (int a = 0; a < 2; ++a)
; #pragma unroll
;             for (int b = 0; b < 2; ++b)
; #pragma unroll
;                 for (int m = 0; m < 4; ++m)
; #pragma unroll
;                     for (int n = 0; n < 2; ++n) acc[a][b][m][n] = (f32x4){0.f, 0.f, 0.f, 0.f};
;         cur = nxt; cA = nA; cB = nB; ++ui;
;         if constexpr (ALIGN_EPI) { if (wr == 1) PG8_BAR; }
	v_exp_f32_e32 v51, v51
	v_rcp_f32_e32 v48, v48
	v_rcp_f32_e32 v49, v49
	v_add_f32_e32 v50, 1.0, v50
	v_add_f32_e32 v51, 1.0, v51
	v_rcp_f32_e32 v50, v50
	v_rcp_f32_e32 v51, v51
	v_pk_mul_f32 v[42:43], v[42:43], v[48:49]
	v_pk_mul_f32 v[40:41], v[46:47], v[40:41]
	v_pk_mul_f32 v[42:43], v[42:43], v[34:35]
	v_pk_mul_f32 v[34:35], v[44:45], v[50:51]
	v_lshl_add_u64 v[46:47], v[52:53], 0, v[114:115]
	v_pk_mul_f32 v[44:45], v[34:35], v[36:37]
	v_cvt_pk_bf16_f32 v34, v38, v39
	v_mul_f32_e32 v38, 0xbfb8aa3b, v30
	v_mul_f32_e32 v39, 0xbfb8aa3b, v31
	v_exp_f32_e32 v38, v38
	v_exp_f32_e32 v39, v39
	v_cvt_pk_bf16_f32 v35, v40, v41
	v_cvt_pk_bf16_f32 v36, v42, v43
	v_cvt_pk_bf16_f32 v37, v44, v45
	global_store_dwordx4 v[46:47], v[34:37], off
	s_nop 1
	v_add_f32_e32 v34, 1.0, v38
	v_add_f32_e32 v35, 1.0, v39
	v_rcp_f32_e32 v34, v34
	v_rcp_f32_e32 v35, v35
	v_add_u32_e32 v36, 0xa0, v149
	v_mad_i64_i32 v[36:37], s[20:21], v36, s98, v[144:145]
	v_pk_mul_f32 v[30:31], v[30:31], v[34:35]
	v_mul_f32_e32 v34, 0xbfb8aa3b, v32
	v_mul_f32_e32 v35, 0xbfb8aa3b, v33
	v_exp_f32_e32 v34, v34
	v_exp_f32_e32 v35, v35
	v_pk_mul_f32 v[22:23], v[30:31], v[22:23]
	v_add_f32_e32 v30, 1.0, v34
	v_add_f32_e32 v31, 1.0, v35
	v_mul_f32_e32 v34, 0xbfb8aa3b, v26
	v_mul_f32_e32 v35, 0xbfb8aa3b, v27
	v_rcp_f32_e32 v30, v30
	v_rcp_f32_e32 v31, v31
	v_exp_f32_e32 v34, v34
	v_exp_f32_e32 v35, v35
	v_pk_mul_f32 v[30:31], v[32:33], v[30:31]
	v_add_f32_e32 v32, 1.0, v34
	v_add_f32_e32 v33, 1.0, v35
	v_mul_f32_e32 v34, 0xbfb8aa3b, v28
	v_mul_f32_e32 v35, 0xbfb8aa3b, v29
	v_exp_f32_e32 v34, v34
	v_exp_f32_e32 v35, v35
	v_rcp_f32_e32 v32, v32
	v_rcp_f32_e32 v33, v33
	v_add_f32_e32 v34, 1.0, v34
	v_add_f32_e32 v35, 1.0, v35
	v_rcp_f32_e32 v34, v34
	v_rcp_f32_e32 v35, v35
	v_pk_mul_f32 v[26:27], v[26:27], v[32:33]
	v_pk_mul_f32 v[24:25], v[30:31], v[24:25]
	v_pk_mul_f32 v[26:27], v[26:27], v[18:19]
	v_pk_mul_f32 v[18:19], v[28:29], v[34:35]
	v_lshl_add_u64 v[30:31], v[36:37], 0, v[114:115]
	v_pk_mul_f32 v[28:29], v[18:19], v[20:21]
	v_cvt_pk_bf16_f32 v18, v22, v23
	v_mul_f32_e32 v22, 0xbfb8aa3b, v14
	v_mul_f32_e32 v23, 0xbfb8aa3b, v15
	v_exp_f32_e32 v22, v22
	v_exp_f32_e32 v23, v23
	v_cvt_pk_bf16_f32 v19, v24, v25
	v_cvt_pk_bf16_f32 v20, v26, v27
	v_cvt_pk_bf16_f32 v21, v28, v29
	global_store_dwordx4 v[30:31], v[18:21], off
	s_nop 1
	v_add_f32_e32 v18, 1.0, v22
	v_add_f32_e32 v19, 1.0, v23
	v_rcp_f32_e32 v18, v18
	v_rcp_f32_e32 v19, v19
	v_add_u32_e32 v20, 0xb0, v149
	v_mad_i64_i32 v[20:21], s[20:21], v20, s98, v[144:145]
	v_pk_mul_f32 v[14:15], v[14:15], v[18:19]
	v_mul_f32_e32 v18, 0xbfb8aa3b, v16
	v_mul_f32_e32 v19, 0xbfb8aa3b, v17
	v_exp_f32_e32 v18, v18
	v_exp_f32_e32 v19, v19
	v_pk_mul_f32 v[6:7], v[14:15], v[6:7]
	v_add_f32_e32 v14, 1.0, v18
	v_add_f32_e32 v15, 1.0, v19
	v_mul_f32_e32 v18, 0xbfb8aa3b, v10
	v_mul_f32_e32 v19, 0xbfb8aa3b, v11
	v_rcp_f32_e32 v14, v14
	v_rcp_f32_e32 v15, v15
	v_exp_f32_e32 v18, v18
	v_exp_f32_e32 v19, v19
	v_pk_mul_f32 v[14:15], v[16:17], v[14:15]
	v_add_f32_e32 v16, 1.0, v18
	v_add_f32_e32 v17, 1.0, v19
	v_mul_f32_e32 v18, 0xbfb8aa3b, v12
	v_mul_f32_e32 v19, 0xbfb8aa3b, v13
	v_exp_f32_e32 v18, v18
	v_exp_f32_e32 v19, v19
	v_rcp_f32_e32 v16, v16
	v_rcp_f32_e32 v17, v17
	v_add_f32_e32 v18, 1.0, v18
	v_add_f32_e32 v19, 1.0, v19
	v_rcp_f32_e32 v18, v18
	v_rcp_f32_e32 v19, v19
	v_pk_mul_f32 v[10:11], v[10:11], v[16:17]
	v_pk_mul_f32 v[8:9], v[14:15], v[8:9]
	v_pk_mul_f32 v[10:11], v[10:11], v[2:3]
	v_pk_mul_f32 v[2:3], v[12:13], v[18:19]
	v_lshl_add_u64 v[14:15], v[20:21], 0, v[114:115]
	v_pk_mul_f32 v[12:13], v[2:3], v[4:5]
	v_cvt_pk_bf16_f32 v2, v6, v7
	v_cvt_pk_bf16_f32 v3, v8, v9
	v_cvt_pk_bf16_f32 v4, v10, v11
	v_cvt_pk_bf16_f32 v5, v12, v13
	global_store_dwordx4 v[14:15], v[2:5], off
	s_cbranch_vccnz .LBB0_280
	s_branch .LBB0_279
